# P1/P7 SwiGLU epilogues re-emitted by hand: same f32 ops per element, scale/add issued as packed f32 ops (fewer VALU instructions per tile)
# baseline (speedup 1.0000x reference)
.Lgemm_epi0:
	s_mov_b32 s56, 0xbfb8aa3b
	v_lshl_or_b32 v156, s47, 7, v148
	v_ashrrev_i32_e32 v157, 31, v156
	v_lshl_add_u32 v152, s22, 8, v146
	v_lshlrev_b64 v[234:235], 1, v[156:157]
	v_lshl_add_u64 v[234:235], s[4:5], 0, v[234:235]
	s_and_b64 vcc, exec, s[2:3]
	s_mov_b32 s47, s8
	s_mov_b32 s22, s12
	s_mov_b64 s[26:27], s[20:21]
	s_mov_b64 s[24:25], s[14:15]
	v_mad_i64_i32 v[236:237], s[0:1], v152, s46, v[234:235]
	v_pk_mul_f32 v[226:227], v[126:127], s[56:57] op_sel_hi:[1,0]
	v_pk_mul_f32 v[228:229], v[128:129], s[56:57] op_sel_hi:[1,0]
	v_pk_mul_f32 v[230:231], v[122:123], s[56:57] op_sel_hi:[1,0]
	v_pk_mul_f32 v[232:233], v[124:125], s[56:57] op_sel_hi:[1,0]
	v_exp_f32_e32 v226, v226
	v_exp_f32_e32 v227, v227
	v_exp_f32_e32 v228, v228
	v_exp_f32_e32 v229, v229
	v_exp_f32_e32 v230, v230
	v_exp_f32_e32 v231, v231
	v_exp_f32_e32 v232, v232
	v_exp_f32_e32 v233, v233
	v_pk_add_f32 v[226:227], v[226:227], 1.0 op_sel_hi:[1,0]
	v_pk_add_f32 v[228:229], v[228:229], 1.0 op_sel_hi:[1,0]
	v_pk_add_f32 v[230:231], v[230:231], 1.0 op_sel_hi:[1,0]
	v_pk_add_f32 v[232:233], v[232:233], 1.0 op_sel_hi:[1,0]
	v_rcp_f32_e32 v226, v226
	v_rcp_f32_e32 v227, v227
	v_rcp_f32_e32 v228, v228
	v_rcp_f32_e32 v229, v229
	v_rcp_f32_e32 v230, v230
	v_rcp_f32_e32 v231, v231
	v_rcp_f32_e32 v232, v232
	v_rcp_f32_e32 v233, v233
	v_pk_mul_f32 v[126:127], v[126:127], v[226:227]
	v_pk_mul_f32 v[128:129], v[128:129], v[228:229]
	v_pk_mul_f32 v[122:123], v[122:123], v[230:231]
	v_pk_mul_f32 v[124:125], v[124:125], v[232:233]
	v_pk_mul_f32 v[118:119], v[126:127], v[118:119]
	v_pk_mul_f32 v[120:121], v[128:129], v[120:121]
	v_pk_mul_f32 v[114:115], v[122:123], v[114:115]
	v_pk_mul_f32 v[116:117], v[124:125], v[116:117]
	v_cvt_pk_bf16_f32 v118, v118, v119
	v_cvt_pk_bf16_f32 v119, v120, v121
	v_cvt_pk_bf16_f32 v120, v114, v115
	v_cvt_pk_bf16_f32 v121, v116, v117
	global_store_dwordx4 v[236:237], v[118:121], off
	v_add_u32_e32 v153, 16, v152
	v_mad_i64_i32 v[238:239], s[0:1], v153, s46, v[234:235]
	v_pk_mul_f32 v[226:227], v[110:111], s[56:57] op_sel_hi:[1,0]
	v_pk_mul_f32 v[228:229], v[112:113], s[56:57] op_sel_hi:[1,0]
	v_pk_mul_f32 v[230:231], v[106:107], s[56:57] op_sel_hi:[1,0]
	v_pk_mul_f32 v[232:233], v[108:109], s[56:57] op_sel_hi:[1,0]
	v_exp_f32_e32 v226, v226
	v_exp_f32_e32 v227, v227
	v_exp_f32_e32 v228, v228
	v_exp_f32_e32 v229, v229
	v_exp_f32_e32 v230, v230
	v_exp_f32_e32 v231, v231
	v_exp_f32_e32 v232, v232
	v_exp_f32_e32 v233, v233
	v_pk_add_f32 v[226:227], v[226:227], 1.0 op_sel_hi:[1,0]
	v_pk_add_f32 v[228:229], v[228:229], 1.0 op_sel_hi:[1,0]
	v_pk_add_f32 v[230:231], v[230:231], 1.0 op_sel_hi:[1,0]
	v_pk_add_f32 v[232:233], v[232:233], 1.0 op_sel_hi:[1,0]
	v_rcp_f32_e32 v226, v226
	v_rcp_f32_e32 v227, v227
	v_rcp_f32_e32 v228, v228
	v_rcp_f32_e32 v229, v229
	v_rcp_f32_e32 v230, v230
	v_rcp_f32_e32 v231, v231
	v_rcp_f32_e32 v232, v232
	v_rcp_f32_e32 v233, v233
	v_pk_mul_f32 v[110:111], v[110:111], v[226:227]
	v_pk_mul_f32 v[112:113], v[112:113], v[228:229]
	v_pk_mul_f32 v[106:107], v[106:107], v[230:231]
	v_pk_mul_f32 v[108:109], v[108:109], v[232:233]
	v_pk_mul_f32 v[102:103], v[110:111], v[102:103]
	v_pk_mul_f32 v[104:105], v[112:113], v[104:105]
	v_pk_mul_f32 v[98:99], v[106:107], v[98:99]
	v_pk_mul_f32 v[100:101], v[108:109], v[100:101]
	v_cvt_pk_bf16_f32 v102, v102, v103
	v_cvt_pk_bf16_f32 v103, v104, v105
	v_cvt_pk_bf16_f32 v104, v98, v99
	v_cvt_pk_bf16_f32 v105, v100, v101
	global_store_dwordx4 v[238:239], v[102:105], off
	v_add_u32_e32 v153, 32, v152
	v_mad_i64_i32 v[236:237], s[0:1], v153, s46, v[234:235]
	v_pk_mul_f32 v[226:227], v[94:95], s[56:57] op_sel_hi:[1,0]
	v_pk_mul_f32 v[228:229], v[96:97], s[56:57] op_sel_hi:[1,0]
	v_pk_mul_f32 v[230:231], v[90:91], s[56:57] op_sel_hi:[1,0]
	v_pk_mul_f32 v[232:233], v[92:93], s[56:57] op_sel_hi:[1,0]
	v_exp_f32_e32 v226, v226
	v_exp_f32_e32 v227, v227
	v_exp_f32_e32 v228, v228
	v_exp_f32_e32 v229, v229
	v_exp_f32_e32 v230, v230
	v_exp_f32_e32 v231, v231
	v_exp_f32_e32 v232, v232
	v_exp_f32_e32 v233, v233
	v_pk_add_f32 v[226:227], v[226:227], 1.0 op_sel_hi:[1,0]
	v_pk_add_f32 v[228:229], v[228:229], 1.0 op_sel_hi:[1,0]
	v_pk_add_f32 v[230:231], v[230:231], 1.0 op_sel_hi:[1,0]
	v_pk_add_f32 v[232:233], v[232:233], 1.0 op_sel_hi:[1,0]
	v_rcp_f32_e32 v226, v226
	v_rcp_f32_e32 v227, v227
	v_rcp_f32_e32 v228, v228
	v_rcp_f32_e32 v229, v229
	v_rcp_f32_e32 v230, v230
	v_rcp_f32_e32 v231, v231
	v_rcp_f32_e32 v232, v232
	v_rcp_f32_e32 v233, v233
	v_pk_mul_f32 v[94:95], v[94:95], v[226:227]
	v_pk_mul_f32 v[96:97], v[96:97], v[228:229]
	v_pk_mul_f32 v[90:91], v[90:91], v[230:231]
	v_pk_mul_f32 v[92:93], v[92:93], v[232:233]
	v_pk_mul_f32 v[86:87], v[94:95], v[86:87]
	v_pk_mul_f32 v[88:89], v[96:97], v[88:89]
	v_pk_mul_f32 v[82:83], v[90:91], v[82:83]
	v_pk_mul_f32 v[84:85], v[92:93], v[84:85]
	v_cvt_pk_bf16_f32 v86, v86, v87
	v_cvt_pk_bf16_f32 v87, v88, v89
	v_cvt_pk_bf16_f32 v88, v82, v83
	v_cvt_pk_bf16_f32 v89, v84, v85
	global_store_dwordx4 v[236:237], v[86:89], off
	v_add_u32_e32 v153, 48, v152
	v_mad_i64_i32 v[238:239], s[0:1], v153, s46, v[234:235]
	v_pk_mul_f32 v[226:227], v[78:79], s[56:57] op_sel_hi:[1,0]
	v_pk_mul_f32 v[228:229], v[80:81], s[56:57] op_sel_hi:[1,0]
	v_pk_mul_f32 v[230:231], v[74:75], s[56:57] op_sel_hi:[1,0]
	v_pk_mul_f32 v[232:233], v[76:77], s[56:57] op_sel_hi:[1,0]
	v_exp_f32_e32 v226, v226
	v_exp_f32_e32 v227, v227
	v_exp_f32_e32 v228, v228
	v_exp_f32_e32 v229, v229
	v_exp_f32_e32 v230, v230
	v_exp_f32_e32 v231, v231
	v_exp_f32_e32 v232, v232
	v_exp_f32_e32 v233, v233
	v_pk_add_f32 v[226:227], v[226:227], 1.0 op_sel_hi:[1,0]
	v_pk_add_f32 v[228:229], v[228:229], 1.0 op_sel_hi:[1,0]
	v_pk_add_f32 v[230:231], v[230:231], 1.0 op_sel_hi:[1,0]
	v_pk_add_f32 v[232:233], v[232:233], 1.0 op_sel_hi:[1,0]
	v_rcp_f32_e32 v226, v226
	v_rcp_f32_e32 v227, v227
	v_rcp_f32_e32 v228, v228
	v_rcp_f32_e32 v229, v229
	v_rcp_f32_e32 v230, v230
	v_rcp_f32_e32 v231, v231
	v_rcp_f32_e32 v232, v232
	v_rcp_f32_e32 v233, v233
	v_pk_mul_f32 v[78:79], v[78:79], v[226:227]
	v_pk_mul_f32 v[80:81], v[80:81], v[228:229]
	v_pk_mul_f32 v[74:75], v[74:75], v[230:231]
	v_pk_mul_f32 v[76:77], v[76:77], v[232:233]
	v_pk_mul_f32 v[70:71], v[78:79], v[70:71]
	v_pk_mul_f32 v[72:73], v[80:81], v[72:73]
	v_pk_mul_f32 v[66:67], v[74:75], v[66:67]
	v_pk_mul_f32 v[68:69], v[76:77], v[68:69]
	v_cvt_pk_bf16_f32 v70, v70, v71
	v_cvt_pk_bf16_f32 v71, v72, v73
	v_cvt_pk_bf16_f32 v72, v66, v67
	v_cvt_pk_bf16_f32 v73, v68, v69
	global_store_dwordx4 v[238:239], v[70:73], off
	v_add_u32_e32 v153, 128, v152
	v_mad_i64_i32 v[236:237], s[0:1], v153, s46, v[234:235]
	v_pk_mul_f32 v[226:227], v[62:63], s[56:57] op_sel_hi:[1,0]
	v_pk_mul_f32 v[228:229], v[64:65], s[56:57] op_sel_hi:[1,0]
	v_pk_mul_f32 v[230:231], v[58:59], s[56:57] op_sel_hi:[1,0]
	v_pk_mul_f32 v[232:233], v[60:61], s[56:57] op_sel_hi:[1,0]
	v_exp_f32_e32 v226, v226
	v_exp_f32_e32 v227, v227
	v_exp_f32_e32 v228, v228
	v_exp_f32_e32 v229, v229
	v_exp_f32_e32 v230, v230
	v_exp_f32_e32 v231, v231
	v_exp_f32_e32 v232, v232
	v_exp_f32_e32 v233, v233
	v_pk_add_f32 v[226:227], v[226:227], 1.0 op_sel_hi:[1,0]
	v_pk_add_f32 v[228:229], v[228:229], 1.0 op_sel_hi:[1,0]
	v_pk_add_f32 v[230:231], v[230:231], 1.0 op_sel_hi:[1,0]
	v_pk_add_f32 v[232:233], v[232:233], 1.0 op_sel_hi:[1,0]
	v_rcp_f32_e32 v226, v226
	v_rcp_f32_e32 v227, v227
	v_rcp_f32_e32 v228, v228
	v_rcp_f32_e32 v229, v229
	v_rcp_f32_e32 v230, v230
	v_rcp_f32_e32 v231, v231
	v_rcp_f32_e32 v232, v232
	v_rcp_f32_e32 v233, v233
	v_pk_mul_f32 v[62:63], v[62:63], v[226:227]
	v_pk_mul_f32 v[64:65], v[64:65], v[228:229]
	v_pk_mul_f32 v[58:59], v[58:59], v[230:231]
	v_pk_mul_f32 v[60:61], v[60:61], v[232:233]
	v_pk_mul_f32 v[54:55], v[62:63], v[54:55]
	v_pk_mul_f32 v[56:57], v[64:65], v[56:57]
	v_pk_mul_f32 v[50:51], v[58:59], v[50:51]
	v_pk_mul_f32 v[52:53], v[60:61], v[52:53]
	v_cvt_pk_bf16_f32 v54, v54, v55
	v_cvt_pk_bf16_f32 v55, v56, v57
	v_cvt_pk_bf16_f32 v56, v50, v51
	v_cvt_pk_bf16_f32 v57, v52, v53
	global_store_dwordx4 v[236:237], v[54:57], off
	v_add_u32_e32 v153, 144, v152
	v_mad_i64_i32 v[238:239], s[0:1], v153, s46, v[234:235]
	v_pk_mul_f32 v[226:227], v[46:47], s[56:57] op_sel_hi:[1,0]
	v_pk_mul_f32 v[228:229], v[48:49], s[56:57] op_sel_hi:[1,0]
	v_pk_mul_f32 v[230:231], v[42:43], s[56:57] op_sel_hi:[1,0]
	v_pk_mul_f32 v[232:233], v[44:45], s[56:57] op_sel_hi:[1,0]
	v_exp_f32_e32 v226, v226
	v_exp_f32_e32 v227, v227
	v_exp_f32_e32 v228, v228
	v_exp_f32_e32 v229, v229
	v_exp_f32_e32 v230, v230
	v_exp_f32_e32 v231, v231
	v_exp_f32_e32 v232, v232
	v_exp_f32_e32 v233, v233
	v_pk_add_f32 v[226:227], v[226:227], 1.0 op_sel_hi:[1,0]
	v_pk_add_f32 v[228:229], v[228:229], 1.0 op_sel_hi:[1,0]
	v_pk_add_f32 v[230:231], v[230:231], 1.0 op_sel_hi:[1,0]
	v_pk_add_f32 v[232:233], v[232:233], 1.0 op_sel_hi:[1,0]
	v_rcp_f32_e32 v226, v226
	v_rcp_f32_e32 v227, v227
	v_rcp_f32_e32 v228, v228
	v_rcp_f32_e32 v229, v229
	v_rcp_f32_e32 v230, v230
	v_rcp_f32_e32 v231, v231
	v_rcp_f32_e32 v232, v232
	v_rcp_f32_e32 v233, v233
	v_pk_mul_f32 v[46:47], v[46:47], v[226:227]
	v_pk_mul_f32 v[48:49], v[48:49], v[228:229]
	v_pk_mul_f32 v[42:43], v[42:43], v[230:231]
	v_pk_mul_f32 v[44:45], v[44:45], v[232:233]
	v_pk_mul_f32 v[38:39], v[46:47], v[38:39]
	v_pk_mul_f32 v[40:41], v[48:49], v[40:41]
	v_pk_mul_f32 v[34:35], v[42:43], v[34:35]
	v_pk_mul_f32 v[36:37], v[44:45], v[36:37]
	v_cvt_pk_bf16_f32 v38, v38, v39
	v_cvt_pk_bf16_f32 v39, v40, v41
	v_cvt_pk_bf16_f32 v40, v34, v35
	v_cvt_pk_bf16_f32 v41, v36, v37
	global_store_dwordx4 v[238:239], v[38:41], off
	v_add_u32_e32 v153, 160, v152
	v_mad_i64_i32 v[236:237], s[0:1], v153, s46, v[234:235]
	v_pk_mul_f32 v[226:227], v[30:31], s[56:57] op_sel_hi:[1,0]
	v_pk_mul_f32 v[228:229], v[32:33], s[56:57] op_sel_hi:[1,0]
	v_pk_mul_f32 v[230:231], v[26:27], s[56:57] op_sel_hi:[1,0]
	v_pk_mul_f32 v[232:233], v[28:29], s[56:57] op_sel_hi:[1,0]
	v_exp_f32_e32 v226, v226
	v_exp_f32_e32 v227, v227
	v_exp_f32_e32 v228, v228
	v_exp_f32_e32 v229, v229
	v_exp_f32_e32 v230, v230
	v_exp_f32_e32 v231, v231
	v_exp_f32_e32 v232, v232
	v_exp_f32_e32 v233, v233
	v_pk_add_f32 v[226:227], v[226:227], 1.0 op_sel_hi:[1,0]
	v_pk_add_f32 v[228:229], v[228:229], 1.0 op_sel_hi:[1,0]
	v_pk_add_f32 v[230:231], v[230:231], 1.0 op_sel_hi:[1,0]
	v_pk_add_f32 v[232:233], v[232:233], 1.0 op_sel_hi:[1,0]
	v_rcp_f32_e32 v226, v226
	v_rcp_f32_e32 v227, v227
	v_rcp_f32_e32 v228, v228
	v_rcp_f32_e32 v229, v229
	v_rcp_f32_e32 v230, v230
	v_rcp_f32_e32 v231, v231
	v_rcp_f32_e32 v232, v232
	v_rcp_f32_e32 v233, v233
	v_pk_mul_f32 v[30:31], v[30:31], v[226:227]
	v_pk_mul_f32 v[32:33], v[32:33], v[228:229]
	v_pk_mul_f32 v[26:27], v[26:27], v[230:231]
	v_pk_mul_f32 v[28:29], v[28:29], v[232:233]
	v_pk_mul_f32 v[22:23], v[30:31], v[22:23]
	v_pk_mul_f32 v[24:25], v[32:33], v[24:25]
	v_pk_mul_f32 v[18:19], v[26:27], v[18:19]
	v_pk_mul_f32 v[20:21], v[28:29], v[20:21]
	v_cvt_pk_bf16_f32 v22, v22, v23
	v_cvt_pk_bf16_f32 v23, v24, v25
	v_cvt_pk_bf16_f32 v24, v18, v19
	v_cvt_pk_bf16_f32 v25, v20, v21
	global_store_dwordx4 v[236:237], v[22:25], off
	v_add_u32_e32 v153, 176, v152
	v_mad_i64_i32 v[238:239], s[0:1], v153, s46, v[234:235]
	v_pk_mul_f32 v[226:227], v[14:15], s[56:57] op_sel_hi:[1,0]
	v_pk_mul_f32 v[228:229], v[16:17], s[56:57] op_sel_hi:[1,0]
	v_pk_mul_f32 v[230:231], v[10:11], s[56:57] op_sel_hi:[1,0]
	v_pk_mul_f32 v[232:233], v[12:13], s[56:57] op_sel_hi:[1,0]
	v_exp_f32_e32 v226, v226
	v_exp_f32_e32 v227, v227
	v_exp_f32_e32 v228, v228
	v_exp_f32_e32 v229, v229
	v_exp_f32_e32 v230, v230
	v_exp_f32_e32 v231, v231
	v_exp_f32_e32 v232, v232
	v_exp_f32_e32 v233, v233
	v_pk_add_f32 v[226:227], v[226:227], 1.0 op_sel_hi:[1,0]
	v_pk_add_f32 v[228:229], v[228:229], 1.0 op_sel_hi:[1,0]
	v_pk_add_f32 v[230:231], v[230:231], 1.0 op_sel_hi:[1,0]
	v_pk_add_f32 v[232:233], v[232:233], 1.0 op_sel_hi:[1,0]
	v_rcp_f32_e32 v226, v226
	v_rcp_f32_e32 v227, v227
	v_rcp_f32_e32 v228, v228
	v_rcp_f32_e32 v229, v229
	v_rcp_f32_e32 v230, v230
	v_rcp_f32_e32 v231, v231
	v_rcp_f32_e32 v232, v232
	v_rcp_f32_e32 v233, v233
	v_pk_mul_f32 v[14:15], v[14:15], v[226:227]
	v_pk_mul_f32 v[16:17], v[16:17], v[228:229]
	v_pk_mul_f32 v[10:11], v[10:11], v[230:231]
	v_pk_mul_f32 v[12:13], v[12:13], v[232:233]
	v_pk_mul_f32 v[6:7], v[14:15], v[6:7]
	v_pk_mul_f32 v[8:9], v[16:17], v[8:9]
	v_pk_mul_f32 v[2:3], v[10:11], v[2:3]
	v_pk_mul_f32 v[4:5], v[12:13], v[4:5]
	v_cvt_pk_bf16_f32 v6, v6, v7
	v_cvt_pk_bf16_f32 v7, v8, v9
	v_cvt_pk_bf16_f32 v8, v2, v3
	v_cvt_pk_bf16_f32 v9, v4, v5
	global_store_dwordx4 v[238:239], v[6:9], off
	s_cbranch_vccz .LBB0_72
	s_waitcnt vmcnt(0)
	s_cmpk_gt_u32 s30, 0xff
	s_cbranch_scc1 .LBB0_79
	s_barrier

.Lgemm_epi4:
	s_mov_b32 s56, 0xbfb8aa3b
	v_lshl_add_u32 v146, s43, 10, v154
	ds_read2_b32 v[234:235], v146 offset1:16
	ds_read2_b32 v[236:237], v146 offset0:32 offset1:48
	ds_read2_b32 v[238:239], v146 offset0:128 offset1:144
	ds_read2_b32 v[240:241], v146 offset0:160 offset1:176
	v_lshl_or_b32 v162, s44, 7, v155
	v_ashrrev_i32_e32 v163, 31, v162
	v_lshl_add_u32 v159, s18, 8, v152
	v_lshlrev_b64 v[242:243], 1, v[162:163]
	v_lshl_add_u64 v[242:243], s[4:5], 0, v[242:243]
	s_and_b64 vcc, exec, s[2:3]
	s_mov_b32 s44, s8
	s_mov_b32 s18, s12
	s_mov_b64 s[22:23], s[16:17]
	s_mov_b64 s[20:21], s[14:15]
	s_mov_b32 s43, s42
	s_waitcnt lgkmcnt(0)
	v_mad_i64_i32 v[244:245], s[0:1], v159, s41, v[242:243]
	v_pk_mul_f32 v[126:127], v[126:127], v[234:235] op_sel_hi:[1,0]
	v_pk_mul_f32 v[128:129], v[128:129], v[234:235] op_sel_hi:[1,0]
	v_pk_mul_f32 v[122:123], v[122:123], v[234:235] op_sel_hi:[1,0]
	v_pk_mul_f32 v[124:125], v[124:125], v[234:235] op_sel_hi:[1,0]
	v_pk_mul_f32 v[118:119], v[118:119], v[234:235] op_sel_hi:[1,0]
	v_pk_mul_f32 v[120:121], v[120:121], v[234:235] op_sel_hi:[1,0]
	v_pk_mul_f32 v[114:115], v[114:115], v[234:235] op_sel_hi:[1,0]
	v_pk_mul_f32 v[116:117], v[116:117], v[234:235] op_sel_hi:[1,0]
	v_pk_mul_f32 v[226:227], v[126:127], s[56:57] op_sel_hi:[1,0]
	v_pk_mul_f32 v[228:229], v[128:129], s[56:57] op_sel_hi:[1,0]
	v_pk_mul_f32 v[230:231], v[122:123], s[56:57] op_sel_hi:[1,0]
	v_pk_mul_f32 v[232:233], v[124:125], s[56:57] op_sel_hi:[1,0]
	v_exp_f32_e32 v226, v226
	v_exp_f32_e32 v227, v227
	v_exp_f32_e32 v228, v228
	v_exp_f32_e32 v229, v229
	v_exp_f32_e32 v230, v230
	v_exp_f32_e32 v231, v231
	v_exp_f32_e32 v232, v232
	v_exp_f32_e32 v233, v233
	v_pk_add_f32 v[226:227], v[226:227], 1.0 op_sel_hi:[1,0]
	v_pk_add_f32 v[228:229], v[228:229], 1.0 op_sel_hi:[1,0]
	v_pk_add_f32 v[230:231], v[230:231], 1.0 op_sel_hi:[1,0]
	v_pk_add_f32 v[232:233], v[232:233], 1.0 op_sel_hi:[1,0]
	v_rcp_f32_e32 v226, v226
	v_rcp_f32_e32 v227, v227
	v_rcp_f32_e32 v228, v228
	v_rcp_f32_e32 v229, v229
	v_rcp_f32_e32 v230, v230
	v_rcp_f32_e32 v231, v231
	v_rcp_f32_e32 v232, v232
	v_rcp_f32_e32 v233, v233
	v_pk_mul_f32 v[126:127], v[126:127], v[226:227]
	v_pk_mul_f32 v[128:129], v[128:129], v[228:229]
	v_pk_mul_f32 v[122:123], v[122:123], v[230:231]
	v_pk_mul_f32 v[124:125], v[124:125], v[232:233]
	v_pk_mul_f32 v[118:119], v[126:127], v[118:119]
	v_pk_mul_f32 v[120:121], v[128:129], v[120:121]
	v_pk_mul_f32 v[114:115], v[122:123], v[114:115]
	v_pk_mul_f32 v[116:117], v[124:125], v[116:117]
	v_cvt_pk_bf16_f32 v118, v118, v119
	v_cvt_pk_bf16_f32 v119, v120, v121
	v_cvt_pk_bf16_f32 v120, v114, v115
	v_cvt_pk_bf16_f32 v121, v116, v117
	global_store_dwordx4 v[244:245], v[118:121], off
	v_add_u32_e32 v160, 16, v159
	v_mad_i64_i32 v[164:165], s[0:1], v160, s41, v[242:243]
	v_pk_mul_f32 v[110:111], v[110:111], v[234:235] op_sel:[0,1] op_sel_hi:[1,1]
	v_pk_mul_f32 v[112:113], v[112:113], v[234:235] op_sel:[0,1] op_sel_hi:[1,1]
	v_pk_mul_f32 v[106:107], v[106:107], v[234:235] op_sel:[0,1] op_sel_hi:[1,1]
	v_pk_mul_f32 v[108:109], v[108:109], v[234:235] op_sel:[0,1] op_sel_hi:[1,1]
	v_pk_mul_f32 v[102:103], v[102:103], v[234:235] op_sel:[0,1] op_sel_hi:[1,1]
	v_pk_mul_f32 v[104:105], v[104:105], v[234:235] op_sel:[0,1] op_sel_hi:[1,1]
	v_pk_mul_f32 v[98:99], v[98:99], v[234:235] op_sel:[0,1] op_sel_hi:[1,1]
	v_pk_mul_f32 v[100:101], v[100:101], v[234:235] op_sel:[0,1] op_sel_hi:[1,1]
	v_pk_mul_f32 v[226:227], v[110:111], s[56:57] op_sel_hi:[1,0]
	v_pk_mul_f32 v[228:229], v[112:113], s[56:57] op_sel_hi:[1,0]
	v_pk_mul_f32 v[230:231], v[106:107], s[56:57] op_sel_hi:[1,0]
	v_pk_mul_f32 v[232:233], v[108:109], s[56:57] op_sel_hi:[1,0]
	v_exp_f32_e32 v226, v226
	v_exp_f32_e32 v227, v227
	v_exp_f32_e32 v228, v228
	v_exp_f32_e32 v229, v229
	v_exp_f32_e32 v230, v230
	v_exp_f32_e32 v231, v231
	v_exp_f32_e32 v232, v232
	v_exp_f32_e32 v233, v233
	v_pk_add_f32 v[226:227], v[226:227], 1.0 op_sel_hi:[1,0]
	v_pk_add_f32 v[228:229], v[228:229], 1.0 op_sel_hi:[1,0]
	v_pk_add_f32 v[230:231], v[230:231], 1.0 op_sel_hi:[1,0]
	v_pk_add_f32 v[232:233], v[232:233], 1.0 op_sel_hi:[1,0]
	v_rcp_f32_e32 v226, v226
	v_rcp_f32_e32 v227, v227
	v_rcp_f32_e32 v228, v228
	v_rcp_f32_e32 v229, v229
	v_rcp_f32_e32 v230, v230
	v_rcp_f32_e32 v231, v231
	v_rcp_f32_e32 v232, v232
	v_rcp_f32_e32 v233, v233
	v_pk_mul_f32 v[110:111], v[110:111], v[226:227]
	v_pk_mul_f32 v[112:113], v[112:113], v[228:229]
	v_pk_mul_f32 v[106:107], v[106:107], v[230:231]
	v_pk_mul_f32 v[108:109], v[108:109], v[232:233]
	v_pk_mul_f32 v[102:103], v[110:111], v[102:103]
	v_pk_mul_f32 v[104:105], v[112:113], v[104:105]
	v_pk_mul_f32 v[98:99], v[106:107], v[98:99]
	v_pk_mul_f32 v[100:101], v[108:109], v[100:101]
	v_cvt_pk_bf16_f32 v102, v102, v103
	v_cvt_pk_bf16_f32 v103, v104, v105
	v_cvt_pk_bf16_f32 v104, v98, v99
	v_cvt_pk_bf16_f32 v105, v100, v101
	global_store_dwordx4 v[164:165], v[102:105], off
	v_add_u32_e32 v160, 32, v159
	v_mad_i64_i32 v[244:245], s[0:1], v160, s41, v[242:243]
	v_pk_mul_f32 v[94:95], v[94:95], v[236:237] op_sel_hi:[1,0]
	v_pk_mul_f32 v[96:97], v[96:97], v[236:237] op_sel_hi:[1,0]
	v_pk_mul_f32 v[90:91], v[90:91], v[236:237] op_sel_hi:[1,0]
	v_pk_mul_f32 v[92:93], v[92:93], v[236:237] op_sel_hi:[1,0]
	v_pk_mul_f32 v[86:87], v[86:87], v[236:237] op_sel_hi:[1,0]
	v_pk_mul_f32 v[88:89], v[88:89], v[236:237] op_sel_hi:[1,0]
	v_pk_mul_f32 v[82:83], v[82:83], v[236:237] op_sel_hi:[1,0]
	v_pk_mul_f32 v[84:85], v[84:85], v[236:237] op_sel_hi:[1,0]
	v_pk_mul_f32 v[226:227], v[94:95], s[56:57] op_sel_hi:[1,0]
	v_pk_mul_f32 v[228:229], v[96:97], s[56:57] op_sel_hi:[1,0]
	v_pk_mul_f32 v[230:231], v[90:91], s[56:57] op_sel_hi:[1,0]
	v_pk_mul_f32 v[232:233], v[92:93], s[56:57] op_sel_hi:[1,0]
	v_exp_f32_e32 v226, v226
	v_exp_f32_e32 v227, v227
	v_exp_f32_e32 v228, v228
	v_exp_f32_e32 v229, v229
	v_exp_f32_e32 v230, v230
	v_exp_f32_e32 v231, v231
	v_exp_f32_e32 v232, v232
	v_exp_f32_e32 v233, v233
	v_pk_add_f32 v[226:227], v[226:227], 1.0 op_sel_hi:[1,0]
	v_pk_add_f32 v[228:229], v[228:229], 1.0 op_sel_hi:[1,0]
	v_pk_add_f32 v[230:231], v[230:231], 1.0 op_sel_hi:[1,0]
	v_pk_add_f32 v[232:233], v[232:233], 1.0 op_sel_hi:[1,0]
	v_rcp_f32_e32 v226, v226
	v_rcp_f32_e32 v227, v227
	v_rcp_f32_e32 v228, v228
	v_rcp_f32_e32 v229, v229
	v_rcp_f32_e32 v230, v230
	v_rcp_f32_e32 v231, v231
	v_rcp_f32_e32 v232, v232
	v_rcp_f32_e32 v233, v233
	v_pk_mul_f32 v[94:95], v[94:95], v[226:227]
	v_pk_mul_f32 v[96:97], v[96:97], v[228:229]
	v_pk_mul_f32 v[90:91], v[90:91], v[230:231]
	v_pk_mul_f32 v[92:93], v[92:93], v[232:233]
	v_pk_mul_f32 v[86:87], v[94:95], v[86:87]
	v_pk_mul_f32 v[88:89], v[96:97], v[88:89]
	v_pk_mul_f32 v[82:83], v[90:91], v[82:83]
	v_pk_mul_f32 v[84:85], v[92:93], v[84:85]
	v_cvt_pk_bf16_f32 v86, v86, v87
	v_cvt_pk_bf16_f32 v87, v88, v89
	v_cvt_pk_bf16_f32 v88, v82, v83
	v_cvt_pk_bf16_f32 v89, v84, v85
	global_store_dwordx4 v[244:245], v[86:89], off
	v_add_u32_e32 v160, 48, v159
	v_mad_i64_i32 v[164:165], s[0:1], v160, s41, v[242:243]
	v_pk_mul_f32 v[78:79], v[78:79], v[236:237] op_sel:[0,1] op_sel_hi:[1,1]
	v_pk_mul_f32 v[80:81], v[80:81], v[236:237] op_sel:[0,1] op_sel_hi:[1,1]
	v_pk_mul_f32 v[74:75], v[74:75], v[236:237] op_sel:[0,1] op_sel_hi:[1,1]
	v_pk_mul_f32 v[76:77], v[76:77], v[236:237] op_sel:[0,1] op_sel_hi:[1,1]
	v_pk_mul_f32 v[70:71], v[70:71], v[236:237] op_sel:[0,1] op_sel_hi:[1,1]
	v_pk_mul_f32 v[72:73], v[72:73], v[236:237] op_sel:[0,1] op_sel_hi:[1,1]
	v_pk_mul_f32 v[66:67], v[66:67], v[236:237] op_sel:[0,1] op_sel_hi:[1,1]
	v_pk_mul_f32 v[68:69], v[68:69], v[236:237] op_sel:[0,1] op_sel_hi:[1,1]
	v_pk_mul_f32 v[226:227], v[78:79], s[56:57] op_sel_hi:[1,0]
	v_pk_mul_f32 v[228:229], v[80:81], s[56:57] op_sel_hi:[1,0]
	v_pk_mul_f32 v[230:231], v[74:75], s[56:57] op_sel_hi:[1,0]
	v_pk_mul_f32 v[232:233], v[76:77], s[56:57] op_sel_hi:[1,0]
	v_exp_f32_e32 v226, v226
	v_exp_f32_e32 v227, v227
	v_exp_f32_e32 v228, v228
	v_exp_f32_e32 v229, v229
	v_exp_f32_e32 v230, v230
	v_exp_f32_e32 v231, v231
	v_exp_f32_e32 v232, v232
	v_exp_f32_e32 v233, v233
	v_pk_add_f32 v[226:227], v[226:227], 1.0 op_sel_hi:[1,0]
	v_pk_add_f32 v[228:229], v[228:229], 1.0 op_sel_hi:[1,0]
	v_pk_add_f32 v[230:231], v[230:231], 1.0 op_sel_hi:[1,0]
	v_pk_add_f32 v[232:233], v[232:233], 1.0 op_sel_hi:[1,0]
	v_rcp_f32_e32 v226, v226
	v_rcp_f32_e32 v227, v227
	v_rcp_f32_e32 v228, v228
	v_rcp_f32_e32 v229, v229
	v_rcp_f32_e32 v230, v230
	v_rcp_f32_e32 v231, v231
	v_rcp_f32_e32 v232, v232
	v_rcp_f32_e32 v233, v233
	v_pk_mul_f32 v[78:79], v[78:79], v[226:227]
	v_pk_mul_f32 v[80:81], v[80:81], v[228:229]
	v_pk_mul_f32 v[74:75], v[74:75], v[230:231]
	v_pk_mul_f32 v[76:77], v[76:77], v[232:233]
	v_pk_mul_f32 v[70:71], v[78:79], v[70:71]
	v_pk_mul_f32 v[72:73], v[80:81], v[72:73]
	v_pk_mul_f32 v[66:67], v[74:75], v[66:67]
	v_pk_mul_f32 v[68:69], v[76:77], v[68:69]
	v_cvt_pk_bf16_f32 v70, v70, v71
	v_cvt_pk_bf16_f32 v71, v72, v73
	v_cvt_pk_bf16_f32 v72, v66, v67
	v_cvt_pk_bf16_f32 v73, v68, v69
	global_store_dwordx4 v[164:165], v[70:73], off
	v_add_u32_e32 v160, 128, v159
	v_mad_i64_i32 v[244:245], s[0:1], v160, s41, v[242:243]
	v_pk_mul_f32 v[62:63], v[62:63], v[238:239] op_sel_hi:[1,0]
	v_pk_mul_f32 v[64:65], v[64:65], v[238:239] op_sel_hi:[1,0]
	v_pk_mul_f32 v[58:59], v[58:59], v[238:239] op_sel_hi:[1,0]
	v_pk_mul_f32 v[60:61], v[60:61], v[238:239] op_sel_hi:[1,0]
	v_pk_mul_f32 v[54:55], v[54:55], v[238:239] op_sel_hi:[1,0]
	v_pk_mul_f32 v[56:57], v[56:57], v[238:239] op_sel_hi:[1,0]
	v_pk_mul_f32 v[50:51], v[50:51], v[238:239] op_sel_hi:[1,0]
	v_pk_mul_f32 v[52:53], v[52:53], v[238:239] op_sel_hi:[1,0]
	v_pk_mul_f32 v[226:227], v[62:63], s[56:57] op_sel_hi:[1,0]
	v_pk_mul_f32 v[228:229], v[64:65], s[56:57] op_sel_hi:[1,0]
	v_pk_mul_f32 v[230:231], v[58:59], s[56:57] op_sel_hi:[1,0]
	v_pk_mul_f32 v[232:233], v[60:61], s[56:57] op_sel_hi:[1,0]
	v_exp_f32_e32 v226, v226
	v_exp_f32_e32 v227, v227
	v_exp_f32_e32 v228, v228
	v_exp_f32_e32 v229, v229
	v_exp_f32_e32 v230, v230
	v_exp_f32_e32 v231, v231
	v_exp_f32_e32 v232, v232
	v_exp_f32_e32 v233, v233
	v_pk_add_f32 v[226:227], v[226:227], 1.0 op_sel_hi:[1,0]
	v_pk_add_f32 v[228:229], v[228:229], 1.0 op_sel_hi:[1,0]
	v_pk_add_f32 v[230:231], v[230:231], 1.0 op_sel_hi:[1,0]
	v_pk_add_f32 v[232:233], v[232:233], 1.0 op_sel_hi:[1,0]
	v_rcp_f32_e32 v226, v226
	v_rcp_f32_e32 v227, v227
	v_rcp_f32_e32 v228, v228
	v_rcp_f32_e32 v229, v229
	v_rcp_f32_e32 v230, v230
	v_rcp_f32_e32 v231, v231
	v_rcp_f32_e32 v232, v232
	v_rcp_f32_e32 v233, v233
	v_pk_mul_f32 v[62:63], v[62:63], v[226:227]
	v_pk_mul_f32 v[64:65], v[64:65], v[228:229]
	v_pk_mul_f32 v[58:59], v[58:59], v[230:231]
	v_pk_mul_f32 v[60:61], v[60:61], v[232:233]
	v_pk_mul_f32 v[54:55], v[62:63], v[54:55]
	v_pk_mul_f32 v[56:57], v[64:65], v[56:57]
	v_pk_mul_f32 v[50:51], v[58:59], v[50:51]
	v_pk_mul_f32 v[52:53], v[60:61], v[52:53]
	v_cvt_pk_bf16_f32 v54, v54, v55
	v_cvt_pk_bf16_f32 v55, v56, v57
	v_cvt_pk_bf16_f32 v56, v50, v51
	v_cvt_pk_bf16_f32 v57, v52, v53
	global_store_dwordx4 v[244:245], v[54:57], off
	v_add_u32_e32 v160, 144, v159
	v_mad_i64_i32 v[164:165], s[0:1], v160, s41, v[242:243]
	v_pk_mul_f32 v[46:47], v[46:47], v[238:239] op_sel:[0,1] op_sel_hi:[1,1]
	v_pk_mul_f32 v[48:49], v[48:49], v[238:239] op_sel:[0,1] op_sel_hi:[1,1]
	v_pk_mul_f32 v[42:43], v[42:43], v[238:239] op_sel:[0,1] op_sel_hi:[1,1]
	v_pk_mul_f32 v[44:45], v[44:45], v[238:239] op_sel:[0,1] op_sel_hi:[1,1]
	v_pk_mul_f32 v[38:39], v[38:39], v[238:239] op_sel:[0,1] op_sel_hi:[1,1]
	v_pk_mul_f32 v[40:41], v[40:41], v[238:239] op_sel:[0,1] op_sel_hi:[1,1]
	v_pk_mul_f32 v[34:35], v[34:35], v[238:239] op_sel:[0,1] op_sel_hi:[1,1]
	v_pk_mul_f32 v[36:37], v[36:37], v[238:239] op_sel:[0,1] op_sel_hi:[1,1]
	v_pk_mul_f32 v[226:227], v[46:47], s[56:57] op_sel_hi:[1,0]
	v_pk_mul_f32 v[228:229], v[48:49], s[56:57] op_sel_hi:[1,0]
	v_pk_mul_f32 v[230:231], v[42:43], s[56:57] op_sel_hi:[1,0]
	v_pk_mul_f32 v[232:233], v[44:45], s[56:57] op_sel_hi:[1,0]
	v_exp_f32_e32 v226, v226
	v_exp_f32_e32 v227, v227
	v_exp_f32_e32 v228, v228
	v_exp_f32_e32 v229, v229
	v_exp_f32_e32 v230, v230
	v_exp_f32_e32 v231, v231
	v_exp_f32_e32 v232, v232
	v_exp_f32_e32 v233, v233
	v_pk_add_f32 v[226:227], v[226:227], 1.0 op_sel_hi:[1,0]
	v_pk_add_f32 v[228:229], v[228:229], 1.0 op_sel_hi:[1,0]
	v_pk_add_f32 v[230:231], v[230:231], 1.0 op_sel_hi:[1,0]
	v_pk_add_f32 v[232:233], v[232:233], 1.0 op_sel_hi:[1,0]
	v_rcp_f32_e32 v226, v226
	v_rcp_f32_e32 v227, v227
	v_rcp_f32_e32 v228, v228
	v_rcp_f32_e32 v229, v229
	v_rcp_f32_e32 v230, v230
	v_rcp_f32_e32 v231, v231
	v_rcp_f32_e32 v232, v232
	v_rcp_f32_e32 v233, v233
	v_pk_mul_f32 v[46:47], v[46:47], v[226:227]
	v_pk_mul_f32 v[48:49], v[48:49], v[228:229]
	v_pk_mul_f32 v[42:43], v[42:43], v[230:231]
	v_pk_mul_f32 v[44:45], v[44:45], v[232:233]
	v_pk_mul_f32 v[38:39], v[46:47], v[38:39]
	v_pk_mul_f32 v[40:41], v[48:49], v[40:41]
	v_pk_mul_f32 v[34:35], v[42:43], v[34:35]
	v_pk_mul_f32 v[36:37], v[44:45], v[36:37]
	v_cvt_pk_bf16_f32 v38, v38, v39
	v_cvt_pk_bf16_f32 v39, v40, v41
	v_cvt_pk_bf16_f32 v40, v34, v35
	v_cvt_pk_bf16_f32 v41, v36, v37
	global_store_dwordx4 v[164:165], v[38:41], off
	v_add_u32_e32 v160, 160, v159
	v_mad_i64_i32 v[244:245], s[0:1], v160, s41, v[242:243]
	v_pk_mul_f32 v[30:31], v[30:31], v[240:241] op_sel_hi:[1,0]
	v_pk_mul_f32 v[32:33], v[32:33], v[240:241] op_sel_hi:[1,0]
	v_pk_mul_f32 v[26:27], v[26:27], v[240:241] op_sel_hi:[1,0]
	v_pk_mul_f32 v[28:29], v[28:29], v[240:241] op_sel_hi:[1,0]
	v_pk_mul_f32 v[22:23], v[22:23], v[240:241] op_sel_hi:[1,0]
	v_pk_mul_f32 v[24:25], v[24:25], v[240:241] op_sel_hi:[1,0]
	v_pk_mul_f32 v[18:19], v[18:19], v[240:241] op_sel_hi:[1,0]
	v_pk_mul_f32 v[20:21], v[20:21], v[240:241] op_sel_hi:[1,0]
	v_pk_mul_f32 v[226:227], v[30:31], s[56:57] op_sel_hi:[1,0]
	v_pk_mul_f32 v[228:229], v[32:33], s[56:57] op_sel_hi:[1,0]
	v_pk_mul_f32 v[230:231], v[26:27], s[56:57] op_sel_hi:[1,0]
	v_pk_mul_f32 v[232:233], v[28:29], s[56:57] op_sel_hi:[1,0]
	v_exp_f32_e32 v226, v226
	v_exp_f32_e32 v227, v227
	v_exp_f32_e32 v228, v228
	v_exp_f32_e32 v229, v229
	v_exp_f32_e32 v230, v230
	v_exp_f32_e32 v231, v231
	v_exp_f32_e32 v232, v232
	v_exp_f32_e32 v233, v233
	v_pk_add_f32 v[226:227], v[226:227], 1.0 op_sel_hi:[1,0]
	v_pk_add_f32 v[228:229], v[228:229], 1.0 op_sel_hi:[1,0]
	v_pk_add_f32 v[230:231], v[230:231], 1.0 op_sel_hi:[1,0]
	v_pk_add_f32 v[232:233], v[232:233], 1.0 op_sel_hi:[1,0]
	v_rcp_f32_e32 v226, v226
	v_rcp_f32_e32 v227, v227
	v_rcp_f32_e32 v228, v228
	v_rcp_f32_e32 v229, v229
	v_rcp_f32_e32 v230, v230
	v_rcp_f32_e32 v231, v231
	v_rcp_f32_e32 v232, v232
	v_rcp_f32_e32 v233, v233
	v_pk_mul_f32 v[30:31], v[30:31], v[226:227]
	v_pk_mul_f32 v[32:33], v[32:33], v[228:229]
	v_pk_mul_f32 v[26:27], v[26:27], v[230:231]
	v_pk_mul_f32 v[28:29], v[28:29], v[232:233]
	v_pk_mul_f32 v[22:23], v[30:31], v[22:23]
	v_pk_mul_f32 v[24:25], v[32:33], v[24:25]
	v_pk_mul_f32 v[18:19], v[26:27], v[18:19]
	v_pk_mul_f32 v[20:21], v[28:29], v[20:21]
	v_cvt_pk_bf16_f32 v22, v22, v23
	v_cvt_pk_bf16_f32 v23, v24, v25
	v_cvt_pk_bf16_f32 v24, v18, v19
	v_cvt_pk_bf16_f32 v25, v20, v21
	global_store_dwordx4 v[244:245], v[22:25], off
	v_add_u32_e32 v160, 176, v159
	v_mad_i64_i32 v[164:165], s[0:1], v160, s41, v[242:243]
	v_pk_mul_f32 v[14:15], v[14:15], v[240:241] op_sel:[0,1] op_sel_hi:[1,1]
	v_pk_mul_f32 v[16:17], v[16:17], v[240:241] op_sel:[0,1] op_sel_hi:[1,1]
	v_pk_mul_f32 v[10:11], v[10:11], v[240:241] op_sel:[0,1] op_sel_hi:[1,1]
	v_pk_mul_f32 v[12:13], v[12:13], v[240:241] op_sel:[0,1] op_sel_hi:[1,1]
	v_pk_mul_f32 v[6:7], v[6:7], v[240:241] op_sel:[0,1] op_sel_hi:[1,1]
	v_pk_mul_f32 v[8:9], v[8:9], v[240:241] op_sel:[0,1] op_sel_hi:[1,1]
	v_pk_mul_f32 v[2:3], v[2:3], v[240:241] op_sel:[0,1] op_sel_hi:[1,1]
	v_pk_mul_f32 v[4:5], v[4:5], v[240:241] op_sel:[0,1] op_sel_hi:[1,1]
	v_pk_mul_f32 v[226:227], v[14:15], s[56:57] op_sel_hi:[1,0]
	v_pk_mul_f32 v[228:229], v[16:17], s[56:57] op_sel_hi:[1,0]
	v_pk_mul_f32 v[230:231], v[10:11], s[56:57] op_sel_hi:[1,0]
	v_pk_mul_f32 v[232:233], v[12:13], s[56:57] op_sel_hi:[1,0]
	v_exp_f32_e32 v226, v226
	v_exp_f32_e32 v227, v227
	v_exp_f32_e32 v228, v228
	v_exp_f32_e32 v229, v229
	v_exp_f32_e32 v230, v230
	v_exp_f32_e32 v231, v231
	v_exp_f32_e32 v232, v232
	v_exp_f32_e32 v233, v233
	v_pk_add_f32 v[226:227], v[226:227], 1.0 op_sel_hi:[1,0]
	v_pk_add_f32 v[228:229], v[228:229], 1.0 op_sel_hi:[1,0]
	v_pk_add_f32 v[230:231], v[230:231], 1.0 op_sel_hi:[1,0]
	v_pk_add_f32 v[232:233], v[232:233], 1.0 op_sel_hi:[1,0]
	v_rcp_f32_e32 v226, v226
	v_rcp_f32_e32 v227, v227
	v_rcp_f32_e32 v228, v228
	v_rcp_f32_e32 v229, v229
	v_rcp_f32_e32 v230, v230
	v_rcp_f32_e32 v231, v231
	v_rcp_f32_e32 v232, v232
	v_rcp_f32_e32 v233, v233
	v_pk_mul_f32 v[14:15], v[14:15], v[226:227]
	v_pk_mul_f32 v[16:17], v[16:17], v[228:229]
	v_pk_mul_f32 v[10:11], v[10:11], v[230:231]
	v_pk_mul_f32 v[12:13], v[12:13], v[232:233]
	v_pk_mul_f32 v[6:7], v[14:15], v[6:7]
	v_pk_mul_f32 v[8:9], v[16:17], v[8:9]
	v_pk_mul_f32 v[2:3], v[10:11], v[2:3]
	v_pk_mul_f32 v[4:5], v[12:13], v[4:5]
	v_cvt_pk_bf16_f32 v6, v6, v7
	v_cvt_pk_bf16_f32 v7, v8, v9
	v_cvt_pk_bf16_f32 v8, v2, v3
	v_cvt_pk_bf16_f32 v9, v4, v5
	global_store_dwordx4 v[164:165], v[6:9], off
	s_cbranch_vccz .LBB0_659
	s_waitcnt vmcnt(0)
	s_cmpk_gt_u32 s26, 0xff
	s_cbranch_scc1 .LBB0_666
	s_barrier
